# v56: v35 + first K-loop iteration peeled in P5 and P1 with literal-0 srcC on each accumulator's first MFMA, removing the 128 v_mov zeroing per unit (replaces the v41 zero-hoist)
# speedup vs baseline: 1.0054x; 1.0054x over previous
.LBB0_373:
	s_ashr_i32 s21, s20, 31
	s_lshl_b64 s[22:23], s[20:21], 19
	s_add_u32 s22, s33, s22
	s_addc_u32 s23, s34, s23
	s_and_b64 s[24:25], s[4:5], exec
	s_cselect_b32 s7, s23, s27
	s_cselect_b32 s21, s22, s26
	s_ashr_i32 s19, s18, 31
	s_lshl_b64 s[24:25], s[18:19], 19
	s_add_u32 s24, s46, s24
	s_addc_u32 s25, s47, s25
	s_and_b64 s[30:31], s[4:5], exec
	s_cselect_b32 s19, s25, s29
	s_cselect_b32 s57, s24, s28
	s_add_u32 s26, s26, 0x40080
	s_addc_u32 s27, s27, 0
	s_add_u32 s58, s28, 0x100
	s_addc_u32 s59, s29, 0
	s_mov_b32 s80, -2
	ds_read_b128 v[152:155], v157
	ds_read_b128 v[160:163], v157 offset:1024
	ds_read_b128 v[164:167], v157 offset:2048
	ds_read_b128 v[168:171], v157 offset:3072
	ds_read_b128 v[172:175], v158
	ds_read_b128 v[176:179], v158 offset:1024
	ds_read_b128 v[180:183], v158 offset:2048
	ds_read_b128 v[184:187], v158 offset:3072
	s_add_u32 s28, s26, 0xfffc0080
	s_addc_u32 s29, s27, -1
	s_cmp_eq_u32 s80, 12
	s_cselect_b32 s31, s7, s29
	s_cselect_b32 s30, s21, s28
	s_cselect_b32 s29, s19, s59
	s_cselect_b32 s28, s57, s58
	v_lshl_add_u64 v[222:223], s[26:27], 0, v[144:145]
	s_add_i32 m0, s9, 0xc000
	ds_read_b128 v[188:191], v159
	ds_read_b128 v[192:195], v159 offset:1024
	ds_read_b128 v[196:199], v159 offset:2048
	ds_read_b128 v[200:203], v159 offset:3072
	ds_read_b128 v[204:207], v159 offset:4096
	ds_read_b128 v[210:213], v159 offset:5120
	ds_read_b128 v[214:217], v159 offset:6144
	ds_read_b128 v[218:221], v159 offset:7168
	global_load_lds_dwordx4 v[222:223], off
	v_lshl_add_u64 v[222:223], s[26:27], 0, v[146:147]
	s_add_i32 m0, s9, 0xe000
	s_nop 0
	global_load_lds_dwordx4 v[222:223], off
	s_waitcnt vmcnt(8)
	s_waitcnt lgkmcnt(0)
	s_barrier
	s_setprio 1
	s_waitcnt lgkmcnt(0)
	v_mfma_f32_16x16x32_bf16 v[126:129], v[152:155], v[188:191], 0
	v_mfma_f32_16x16x32_bf16 v[122:125], v[164:167], v[188:191], 0
	v_mfma_f32_16x16x32_bf16 v[110:113], v[152:155], v[196:199], 0
	v_mfma_f32_16x16x32_bf16 v[106:109], v[164:167], v[196:199], 0
	v_mfma_f32_16x16x32_bf16 v[94:97], v[152:155], v[204:207], 0
	v_mfma_f32_16x16x32_bf16 v[90:93], v[164:167], v[204:207], 0
	v_mfma_f32_16x16x32_bf16 v[78:81], v[152:155], v[214:217], 0
	v_mfma_f32_16x16x32_bf16 v[74:77], v[164:167], v[214:217], 0
	v_mfma_f32_16x16x32_bf16 v[126:129], v[160:163], v[192:195], v[126:129]
	v_mfma_f32_16x16x32_bf16 v[122:125], v[168:171], v[192:195], v[122:125]
	v_mfma_f32_16x16x32_bf16 v[110:113], v[160:163], v[200:203], v[110:113]
	v_mfma_f32_16x16x32_bf16 v[106:109], v[168:171], v[200:203], v[106:109]
	v_mfma_f32_16x16x32_bf16 v[94:97], v[160:163], v[210:213], v[94:97]
	v_mfma_f32_16x16x32_bf16 v[90:93], v[168:171], v[210:213], v[90:93]
	v_mfma_f32_16x16x32_bf16 v[78:81], v[160:163], v[218:221], v[78:81]
	v_mfma_f32_16x16x32_bf16 v[74:77], v[168:171], v[218:221], v[74:77]
	s_setprio 0
	s_setprio 1
	v_mfma_f32_16x16x32_bf16 v[118:121], v[172:175], v[188:191], 0
	v_mfma_f32_16x16x32_bf16 v[114:117], v[180:183], v[188:191], 0
	v_mfma_f32_16x16x32_bf16 v[102:105], v[172:175], v[196:199], 0
	v_mfma_f32_16x16x32_bf16 v[98:101], v[180:183], v[196:199], 0
	v_mfma_f32_16x16x32_bf16 v[86:89], v[172:175], v[204:207], 0
	v_mfma_f32_16x16x32_bf16 v[82:85], v[180:183], v[204:207], 0
	v_mfma_f32_16x16x32_bf16 v[70:73], v[172:175], v[214:217], 0
	v_mfma_f32_16x16x32_bf16 v[66:69], v[180:183], v[214:217], 0
	v_mfma_f32_16x16x32_bf16 v[118:121], v[176:179], v[192:195], v[118:121]
	v_mfma_f32_16x16x32_bf16 v[114:117], v[184:187], v[192:195], v[114:117]
	v_mfma_f32_16x16x32_bf16 v[102:105], v[176:179], v[200:203], v[102:105]
	v_mfma_f32_16x16x32_bf16 v[98:101], v[184:187], v[200:203], v[98:101]
	v_mfma_f32_16x16x32_bf16 v[86:89], v[176:179], v[210:213], v[86:89]
	v_mfma_f32_16x16x32_bf16 v[82:85], v[184:187], v[210:213], v[82:85]
	v_mfma_f32_16x16x32_bf16 v[70:73], v[176:179], v[218:221], v[70:73]
	v_mfma_f32_16x16x32_bf16 v[66:69], v[184:187], v[218:221], v[66:69]
	s_setprio 0
	s_barrier
	s_add_i32 s81, s44, s35
	v_lshl_add_u64 v[222:223], s[28:29], 0, v[132:133]
	s_mov_b32 m0, s81
	ds_read_b128 v[188:191], v159 offset:16384
	ds_read_b128 v[192:195], v159 offset:17408
	ds_read_b128 v[196:199], v159 offset:18432
	ds_read_b128 v[200:203], v159 offset:19456
	ds_read_b128 v[204:207], v159 offset:20480
	ds_read_b128 v[210:213], v159 offset:21504
	ds_read_b128 v[214:217], v159 offset:22528
	ds_read_b128 v[218:221], v159 offset:23552
	global_load_lds_dwordx4 v[222:223], off
	s_add_i32 m0, s81, 0x2000
	s_add_u32 s82, s28, 0x40000
	v_lshl_add_u64 v[224:225], s[28:29], 0, v[136:137]
	s_addc_u32 s83, s29, 0
	s_add_i32 s81, s45, s35
	global_load_lds_dwordx4 v[224:225], off
	v_lshl_add_u64 v[226:227], s[82:83], 0, v[132:133]
	s_mov_b32 m0, s81
	v_lshl_add_u64 v[228:229], s[30:31], 0, v[134:135]
	global_load_lds_dwordx4 v[226:227], off
	v_lshl_add_u64 v[226:227], s[82:83], 0, v[136:137]
	s_add_i32 m0, s81, 0x2000
	s_nop 0
	global_load_lds_dwordx4 v[226:227], off
	v_lshl_add_u64 v[226:227], s[30:31], 0, v[130:131]
	s_mov_b32 m0, s9
	s_nop 0
	global_load_lds_dwordx4 v[226:227], off
	s_mov_b32 m0, s36
	s_nop 0
	global_load_lds_dwordx4 v[228:229], off
	s_waitcnt vmcnt(8)
	s_waitcnt lgkmcnt(0)
	s_barrier
	s_setprio 1
	s_waitcnt lgkmcnt(0)
	v_mfma_f32_16x16x32_bf16 v[62:65], v[152:155], v[188:191], 0
	v_mfma_f32_16x16x32_bf16 v[58:61], v[164:167], v[188:191], 0
	v_mfma_f32_16x16x32_bf16 v[46:49], v[152:155], v[196:199], 0
	v_mfma_f32_16x16x32_bf16 v[42:45], v[164:167], v[196:199], 0
	v_mfma_f32_16x16x32_bf16 v[30:33], v[152:155], v[204:207], 0
	v_mfma_f32_16x16x32_bf16 v[26:29], v[164:167], v[204:207], 0
	v_mfma_f32_16x16x32_bf16 v[14:17], v[152:155], v[214:217], 0
	v_mfma_f32_16x16x32_bf16 v[10:13], v[164:167], v[214:217], 0
	v_mfma_f32_16x16x32_bf16 v[62:65], v[160:163], v[192:195], v[62:65]
	v_mfma_f32_16x16x32_bf16 v[58:61], v[168:171], v[192:195], v[58:61]
	v_mfma_f32_16x16x32_bf16 v[46:49], v[160:163], v[200:203], v[46:49]
	v_mfma_f32_16x16x32_bf16 v[42:45], v[168:171], v[200:203], v[42:45]
	v_mfma_f32_16x16x32_bf16 v[30:33], v[160:163], v[210:213], v[30:33]
	v_mfma_f32_16x16x32_bf16 v[26:29], v[168:171], v[210:213], v[26:29]
	v_mfma_f32_16x16x32_bf16 v[14:17], v[160:163], v[218:221], v[14:17]
	v_mfma_f32_16x16x32_bf16 v[10:13], v[168:171], v[218:221], v[10:13]
	s_setprio 0
	s_setprio 1
	v_mfma_f32_16x16x32_bf16 v[54:57], v[172:175], v[188:191], 0
	v_mfma_f32_16x16x32_bf16 v[50:53], v[180:183], v[188:191], 0
	v_mfma_f32_16x16x32_bf16 v[38:41], v[172:175], v[196:199], 0
	v_mfma_f32_16x16x32_bf16 v[34:37], v[180:183], v[196:199], 0
	v_mfma_f32_16x16x32_bf16 v[22:25], v[172:175], v[204:207], 0
	v_mfma_f32_16x16x32_bf16 v[18:21], v[180:183], v[204:207], 0
	v_mfma_f32_16x16x32_bf16 v[6:9], v[172:175], v[214:217], 0
	v_mfma_f32_16x16x32_bf16 v[2:5], v[180:183], v[214:217], 0
	v_mfma_f32_16x16x32_bf16 v[54:57], v[176:179], v[192:195], v[54:57]
	v_mfma_f32_16x16x32_bf16 v[50:53], v[184:187], v[192:195], v[50:53]
	v_mfma_f32_16x16x32_bf16 v[38:41], v[176:179], v[200:203], v[38:41]
	v_mfma_f32_16x16x32_bf16 v[34:37], v[184:187], v[200:203], v[34:37]
	v_mfma_f32_16x16x32_bf16 v[22:25], v[176:179], v[210:213], v[22:25]
	v_mfma_f32_16x16x32_bf16 v[18:21], v[184:187], v[210:213], v[18:21]
	v_mfma_f32_16x16x32_bf16 v[6:9], v[176:179], v[218:221], v[6:9]
	v_mfma_f32_16x16x32_bf16 v[2:5], v[184:187], v[218:221], v[2:5]
	s_setprio 0
	s_barrier
	s_add_i32 s81, 0, 0x18000
	v_add_u32_e32 v138, s81, v156
	s_add_i32 s82, 0, 0x1c000
	ds_read_b128 v[152:155], v138
	ds_read_b128 v[160:163], v138 offset:1024
	ds_read_b128 v[164:167], v138 offset:2048
	ds_read_b128 v[168:171], v138 offset:3072
	v_add_u32_e32 v138, 0x1000, v138
	ds_read_b128 v[172:175], v138
	ds_read_b128 v[176:179], v138 offset:1024
	ds_read_b128 v[180:183], v138 offset:2048
	ds_read_b128 v[184:187], v138 offset:3072
	s_add_u32 s30, s30, 0x40000
	s_addc_u32 s31, s31, 0
	s_mov_b32 m0, s37
	v_lshl_add_u64 v[230:231], s[30:31], 0, v[130:131]
	ds_read_b128 v[188:191], v159 offset:32768
	ds_read_b128 v[192:195], v159 offset:33792
	ds_read_b128 v[196:199], v159 offset:34816
	ds_read_b128 v[200:203], v159 offset:35840
	ds_read_b128 v[204:207], v159 offset:36864
	ds_read_b128 v[210:213], v159 offset:37888
	ds_read_b128 v[214:217], v159 offset:38912
	ds_read_b128 v[218:221], v159 offset:39936
	global_load_lds_dwordx4 v[230:231], off
	v_lshl_add_u64 v[230:231], s[30:31], 0, v[134:135]
	s_mov_b32 m0, s38
	s_nop 0
	global_load_lds_dwordx4 v[230:231], off
	s_waitcnt vmcnt(8)
	s_waitcnt lgkmcnt(0)
	s_barrier
	s_setprio 1
	s_waitcnt lgkmcnt(0)
	v_mfma_f32_16x16x32_bf16 v[126:129], v[152:155], v[188:191], v[126:129]
	v_mfma_f32_16x16x32_bf16 v[122:125], v[164:167], v[188:191], v[122:125]
	v_mfma_f32_16x16x32_bf16 v[110:113], v[152:155], v[196:199], v[110:113]
	v_mfma_f32_16x16x32_bf16 v[106:109], v[164:167], v[196:199], v[106:109]
	v_mfma_f32_16x16x32_bf16 v[94:97], v[152:155], v[204:207], v[94:97]
	v_mfma_f32_16x16x32_bf16 v[90:93], v[164:167], v[204:207], v[90:93]
	v_mfma_f32_16x16x32_bf16 v[78:81], v[152:155], v[214:217], v[78:81]
	v_mfma_f32_16x16x32_bf16 v[74:77], v[164:167], v[214:217], v[74:77]
	v_mfma_f32_16x16x32_bf16 v[126:129], v[160:163], v[192:195], v[126:129]
	v_mfma_f32_16x16x32_bf16 v[122:125], v[168:171], v[192:195], v[122:125]
	v_mfma_f32_16x16x32_bf16 v[110:113], v[160:163], v[200:203], v[110:113]
	v_mfma_f32_16x16x32_bf16 v[106:109], v[168:171], v[200:203], v[106:109]
	v_mfma_f32_16x16x32_bf16 v[94:97], v[160:163], v[210:213], v[94:97]
	v_mfma_f32_16x16x32_bf16 v[90:93], v[168:171], v[210:213], v[90:93]
	v_mfma_f32_16x16x32_bf16 v[78:81], v[160:163], v[218:221], v[78:81]
	v_mfma_f32_16x16x32_bf16 v[74:77], v[168:171], v[218:221], v[74:77]
	s_setprio 0
	s_setprio 1
	v_mfma_f32_16x16x32_bf16 v[118:121], v[172:175], v[188:191], v[118:121]
	v_mfma_f32_16x16x32_bf16 v[114:117], v[180:183], v[188:191], v[114:117]
	v_mfma_f32_16x16x32_bf16 v[102:105], v[172:175], v[196:199], v[102:105]
	v_mfma_f32_16x16x32_bf16 v[98:101], v[180:183], v[196:199], v[98:101]
	v_mfma_f32_16x16x32_bf16 v[86:89], v[172:175], v[204:207], v[86:89]
	v_mfma_f32_16x16x32_bf16 v[82:85], v[180:183], v[204:207], v[82:85]
	v_mfma_f32_16x16x32_bf16 v[70:73], v[172:175], v[214:217], v[70:73]
	v_mfma_f32_16x16x32_bf16 v[66:69], v[180:183], v[214:217], v[66:69]
	v_mfma_f32_16x16x32_bf16 v[118:121], v[176:179], v[192:195], v[118:121]
	v_mfma_f32_16x16x32_bf16 v[114:117], v[184:187], v[192:195], v[114:117]
	v_mfma_f32_16x16x32_bf16 v[102:105], v[176:179], v[200:203], v[102:105]
	v_mfma_f32_16x16x32_bf16 v[98:101], v[184:187], v[200:203], v[98:101]
	v_mfma_f32_16x16x32_bf16 v[86:89], v[176:179], v[210:213], v[86:89]
	v_mfma_f32_16x16x32_bf16 v[82:85], v[184:187], v[210:213], v[82:85]
	v_mfma_f32_16x16x32_bf16 v[70:73], v[176:179], v[218:221], v[70:73]
	v_mfma_f32_16x16x32_bf16 v[66:69], v[184:187], v[218:221], v[66:69]
	s_setprio 0
	s_barrier
	s_add_i32 s30, s81, s35
	v_lshl_add_u64 v[222:223], v[222:223], 0, s[14:15]
	s_mov_b32 m0, s30
	ds_read_b128 v[188:191], v159 offset:49152
	ds_read_b128 v[192:195], v159 offset:50176
	ds_read_b128 v[196:199], v159 offset:51200
	ds_read_b128 v[200:203], v159 offset:52224
	ds_read_b128 v[204:207], v159 offset:53248
	ds_read_b128 v[210:213], v159 offset:54272
	ds_read_b128 v[214:217], v159 offset:55296
	ds_read_b128 v[218:221], v159 offset:56320
	global_load_lds_dwordx4 v[222:223], off
	s_add_i32 m0, s30, 0x2000
	s_add_u32 s28, s28, 0x40080
	v_lshl_add_u64 v[222:223], v[224:225], 0, s[14:15]
	s_addc_u32 s29, s29, 0
	s_add_i32 s30, s82, s35
	global_load_lds_dwordx4 v[222:223], off
	v_lshl_add_u64 v[222:223], s[28:29], 0, v[132:133]
	s_mov_b32 m0, s30
	s_nop 0
	global_load_lds_dwordx4 v[222:223], off
	v_lshl_add_u64 v[222:223], s[28:29], 0, v[136:137]
	s_add_i32 m0, s30, 0x2000
	s_nop 0
	global_load_lds_dwordx4 v[222:223], off
	v_lshl_add_u64 v[222:223], v[226:227], 0, s[14:15]
	s_mov_b32 m0, s40
	s_nop 0
	global_load_lds_dwordx4 v[222:223], off
	v_lshl_add_u64 v[222:223], v[228:229], 0, s[14:15]
	s_mov_b32 m0, s41
	s_nop 0
	global_load_lds_dwordx4 v[222:223], off
	s_waitcnt vmcnt(8)
	s_waitcnt lgkmcnt(0)
	s_barrier
	s_setprio 1
	s_waitcnt lgkmcnt(0)
	v_mfma_f32_16x16x32_bf16 v[62:65], v[152:155], v[188:191], v[62:65]
	v_mfma_f32_16x16x32_bf16 v[58:61], v[164:167], v[188:191], v[58:61]
	v_mfma_f32_16x16x32_bf16 v[46:49], v[152:155], v[196:199], v[46:49]
	v_mfma_f32_16x16x32_bf16 v[42:45], v[164:167], v[196:199], v[42:45]
	v_mfma_f32_16x16x32_bf16 v[30:33], v[152:155], v[204:207], v[30:33]
	v_mfma_f32_16x16x32_bf16 v[26:29], v[164:167], v[204:207], v[26:29]
	v_mfma_f32_16x16x32_bf16 v[14:17], v[152:155], v[214:217], v[14:17]
	v_mfma_f32_16x16x32_bf16 v[10:13], v[164:167], v[214:217], v[10:13]
	v_mfma_f32_16x16x32_bf16 v[62:65], v[160:163], v[192:195], v[62:65]
	v_mfma_f32_16x16x32_bf16 v[58:61], v[168:171], v[192:195], v[58:61]
	v_mfma_f32_16x16x32_bf16 v[46:49], v[160:163], v[200:203], v[46:49]
	v_mfma_f32_16x16x32_bf16 v[42:45], v[168:171], v[200:203], v[42:45]
	v_mfma_f32_16x16x32_bf16 v[30:33], v[160:163], v[210:213], v[30:33]
	v_mfma_f32_16x16x32_bf16 v[26:29], v[168:171], v[210:213], v[26:29]
	v_mfma_f32_16x16x32_bf16 v[14:17], v[160:163], v[218:221], v[14:17]
	v_mfma_f32_16x16x32_bf16 v[10:13], v[168:171], v[218:221], v[10:13]
	s_setprio 0
	s_setprio 1
	v_mfma_f32_16x16x32_bf16 v[54:57], v[172:175], v[188:191], v[54:57]
	v_mfma_f32_16x16x32_bf16 v[50:53], v[180:183], v[188:191], v[50:53]
	v_mfma_f32_16x16x32_bf16 v[38:41], v[172:175], v[196:199], v[38:41]
	v_mfma_f32_16x16x32_bf16 v[34:37], v[180:183], v[196:199], v[34:37]
	v_mfma_f32_16x16x32_bf16 v[22:25], v[172:175], v[204:207], v[22:25]
	v_mfma_f32_16x16x32_bf16 v[18:21], v[180:183], v[204:207], v[18:21]
	v_mfma_f32_16x16x32_bf16 v[6:9], v[172:175], v[214:217], v[6:9]
	v_mfma_f32_16x16x32_bf16 v[2:5], v[180:183], v[214:217], v[2:5]
	v_mfma_f32_16x16x32_bf16 v[54:57], v[176:179], v[192:195], v[54:57]
	v_mfma_f32_16x16x32_bf16 v[50:53], v[184:187], v[192:195], v[50:53]
	v_mfma_f32_16x16x32_bf16 v[38:41], v[176:179], v[200:203], v[38:41]
	v_mfma_f32_16x16x32_bf16 v[34:37], v[184:187], v[200:203], v[34:37]
	v_mfma_f32_16x16x32_bf16 v[22:25], v[176:179], v[210:213], v[22:25]
	v_mfma_f32_16x16x32_bf16 v[18:21], v[184:187], v[210:213], v[18:21]
	v_mfma_f32_16x16x32_bf16 v[6:9], v[176:179], v[218:221], v[6:9]
	v_mfma_f32_16x16x32_bf16 v[2:5], v[184:187], v[218:221], v[2:5]
	s_setprio 0
	s_barrier
	s_add_i32 s80, s80, 2
	s_add_u32 s26, s26, 0x100
	s_addc_u32 s27, s27, 0
	s_add_u32 s58, s58, 0x100
	s_addc_u32 s59, s59, 0
	s_cmp_gt_u32 s80, 13

.LBB0_1557:
	s_ashr_i32 s17, s16, 31
	s_lshl_b64 s[18:19], s[16:17], 19
	s_add_u32 s18, s33, s18
	s_addc_u32 s19, s34, s19
	s_and_b64 s[20:21], s[2:3], exec
	s_cselect_b32 s17, s19, s25
	s_cselect_b32 s51, s18, s24
	s_ashr_i32 s15, s14, 31
	s_lshl_b64 s[20:21], s[14:15], 19
	s_add_u32 s20, s30, s20
	s_addc_u32 s21, s31, s21
	s_and_b64 s[28:29], s[2:3], exec
	s_cselect_b32 s15, s21, s27
	s_cselect_b32 s52, s20, s26
	s_add_u32 s24, s24, 0x40080
	s_addc_u32 s25, s25, 0
	s_add_u32 s53, s26, 0x100
	s_addc_u32 s54, s27, 0
	s_mov_b32 s55, -2
	ds_read_b128 v[146:149], v153
	ds_read_b128 v[156:159], v153 offset:1024
	ds_read_b128 v[160:163], v153 offset:2048
	ds_read_b128 v[164:167], v153 offset:3072
	ds_read_b128 v[168:171], v154
	ds_read_b128 v[172:175], v154 offset:1024
	ds_read_b128 v[180:183], v154 offset:2048
	ds_read_b128 v[184:187], v154 offset:3072
	s_add_u32 s26, s24, 0xfffc0080
	s_addc_u32 s27, s25, -1
	s_cmp_eq_u32 s55, 12
	s_cselect_b32 s29, s17, s27
	s_cselect_b32 s28, s51, s26
	s_cselect_b32 s27, s15, s54
	s_cselect_b32 s26, s52, s53
	v_lshl_add_u64 v[176:177], s[24:25], 0, v[138:139]
	s_add_i32 m0, s23, 0xc000
	ds_read_b128 v[188:191], v155
	ds_read_b128 v[192:195], v155 offset:1024
	ds_read_b128 v[196:199], v155 offset:2048
	ds_read_b128 v[200:203], v155 offset:3072
	ds_read_b128 v[204:207], v155 offset:4096
	ds_read_b128 v[210:213], v155 offset:5120
	ds_read_b128 v[214:217], v155 offset:6144
	ds_read_b128 v[218:221], v155 offset:7168
	global_load_lds_dwordx4 v[176:177], off
	v_lshl_add_u64 v[176:177], s[24:25], 0, v[140:141]
	s_add_i32 m0, s23, 0xe000
	s_nop 0
	global_load_lds_dwordx4 v[176:177], off
	s_waitcnt vmcnt(8)
	s_waitcnt lgkmcnt(0)
	s_barrier
	s_setprio 1
	s_waitcnt lgkmcnt(0)
	v_mfma_f32_16x16x32_bf16 v[122:125], v[146:149], v[188:191], 0
	v_mfma_f32_16x16x32_bf16 v[114:117], v[160:163], v[188:191], 0
	v_mfma_f32_16x16x32_bf16 v[106:109], v[146:149], v[196:199], 0
	v_mfma_f32_16x16x32_bf16 v[98:101], v[160:163], v[196:199], 0
	v_mfma_f32_16x16x32_bf16 v[90:93], v[146:149], v[204:207], 0
	v_mfma_f32_16x16x32_bf16 v[82:85], v[160:163], v[204:207], 0
	v_mfma_f32_16x16x32_bf16 v[74:77], v[146:149], v[214:217], 0
	v_mfma_f32_16x16x32_bf16 v[70:73], v[160:163], v[214:217], 0
	v_mfma_f32_16x16x32_bf16 v[122:125], v[156:159], v[192:195], v[122:125]
	v_mfma_f32_16x16x32_bf16 v[114:117], v[164:167], v[192:195], v[114:117]
	v_mfma_f32_16x16x32_bf16 v[106:109], v[156:159], v[200:203], v[106:109]
	v_mfma_f32_16x16x32_bf16 v[98:101], v[164:167], v[200:203], v[98:101]
	v_mfma_f32_16x16x32_bf16 v[90:93], v[156:159], v[210:213], v[90:93]
	v_mfma_f32_16x16x32_bf16 v[82:85], v[164:167], v[210:213], v[82:85]
	v_mfma_f32_16x16x32_bf16 v[74:77], v[156:159], v[218:221], v[74:77]
	v_mfma_f32_16x16x32_bf16 v[70:73], v[164:167], v[218:221], v[70:73]
	s_setprio 0
	s_setprio 1
	v_mfma_f32_16x16x32_bf16 v[126:129], v[168:171], v[188:191], 0
	v_mfma_f32_16x16x32_bf16 v[118:121], v[180:183], v[188:191], 0
	v_mfma_f32_16x16x32_bf16 v[110:113], v[168:171], v[196:199], 0
	v_mfma_f32_16x16x32_bf16 v[102:105], v[180:183], v[196:199], 0
	v_mfma_f32_16x16x32_bf16 v[94:97], v[168:171], v[204:207], 0
	v_mfma_f32_16x16x32_bf16 v[86:89], v[180:183], v[204:207], 0
	v_mfma_f32_16x16x32_bf16 v[78:81], v[168:171], v[214:217], 0
	v_mfma_f32_16x16x32_bf16 v[66:69], v[180:183], v[214:217], 0
	v_mfma_f32_16x16x32_bf16 v[126:129], v[172:175], v[192:195], v[126:129]
	v_mfma_f32_16x16x32_bf16 v[118:121], v[184:187], v[192:195], v[118:121]
	v_mfma_f32_16x16x32_bf16 v[110:113], v[172:175], v[200:203], v[110:113]
	v_mfma_f32_16x16x32_bf16 v[102:105], v[184:187], v[200:203], v[102:105]
	v_mfma_f32_16x16x32_bf16 v[94:97], v[172:175], v[210:213], v[94:97]
	v_mfma_f32_16x16x32_bf16 v[86:89], v[184:187], v[210:213], v[86:89]
	v_mfma_f32_16x16x32_bf16 v[78:81], v[172:175], v[218:221], v[78:81]
	v_mfma_f32_16x16x32_bf16 v[66:69], v[184:187], v[218:221], v[66:69]
	s_setprio 0
	s_barrier
	s_add_i32 s56, s45, s35
	v_lshl_add_u64 v[176:177], s[26:27], 0, v[134:135]
	s_mov_b32 m0, s56
	ds_read_b128 v[188:191], v155 offset:16384
	ds_read_b128 v[192:195], v155 offset:17408
	ds_read_b128 v[196:199], v155 offset:18432
	ds_read_b128 v[200:203], v155 offset:19456
	ds_read_b128 v[204:207], v155 offset:20480
	ds_read_b128 v[210:213], v155 offset:21504
	ds_read_b128 v[214:217], v155 offset:22528
	ds_read_b128 v[218:221], v155 offset:23552
	global_load_lds_dwordx4 v[176:177], off
	s_add_i32 m0, s56, 0x2000
	s_add_u32 s56, s26, 0x40000
	v_lshl_add_u64 v[208:209], s[26:27], 0, v[130:131]
	s_addc_u32 s57, s27, 0
	s_add_i32 s58, s48, s35
	global_load_lds_dwordx4 v[208:209], off
	v_lshl_add_u64 v[222:223], s[56:57], 0, v[134:135]
	s_mov_b32 m0, s58
	v_lshl_add_u64 v[224:225], s[28:29], 0, v[132:133]
	global_load_lds_dwordx4 v[222:223], off
	v_lshl_add_u64 v[222:223], s[56:57], 0, v[130:131]
	s_add_i32 m0, s58, 0x2000
	s_nop 0
	global_load_lds_dwordx4 v[222:223], off
	v_lshl_add_u64 v[222:223], s[28:29], 0, v[136:137]
	s_mov_b32 m0, s23
	s_nop 0
	global_load_lds_dwordx4 v[222:223], off
	s_mov_b32 m0, s38
	s_nop 0
	global_load_lds_dwordx4 v[224:225], off
	s_waitcnt vmcnt(8)
	s_waitcnt lgkmcnt(0)
	s_barrier
	s_setprio 1
	s_waitcnt lgkmcnt(0)
	v_mfma_f32_16x16x32_bf16 v[58:61], v[146:149], v[188:191], 0
	v_mfma_f32_16x16x32_bf16 v[54:57], v[160:163], v[188:191], 0
	v_mfma_f32_16x16x32_bf16 v[42:45], v[146:149], v[196:199], 0
	v_mfma_f32_16x16x32_bf16 v[38:41], v[160:163], v[196:199], 0
	v_mfma_f32_16x16x32_bf16 v[26:29], v[146:149], v[204:207], 0
	v_mfma_f32_16x16x32_bf16 v[22:25], v[160:163], v[204:207], 0
	v_mfma_f32_16x16x32_bf16 v[10:13], v[146:149], v[214:217], 0
	v_mfma_f32_16x16x32_bf16 v[6:9], v[160:163], v[214:217], 0
	v_mfma_f32_16x16x32_bf16 v[58:61], v[156:159], v[192:195], v[58:61]
	v_mfma_f32_16x16x32_bf16 v[54:57], v[164:167], v[192:195], v[54:57]
	v_mfma_f32_16x16x32_bf16 v[42:45], v[156:159], v[200:203], v[42:45]
	v_mfma_f32_16x16x32_bf16 v[38:41], v[164:167], v[200:203], v[38:41]
	v_mfma_f32_16x16x32_bf16 v[26:29], v[156:159], v[210:213], v[26:29]
	v_mfma_f32_16x16x32_bf16 v[22:25], v[164:167], v[210:213], v[22:25]
	v_mfma_f32_16x16x32_bf16 v[10:13], v[156:159], v[218:221], v[10:13]
	v_mfma_f32_16x16x32_bf16 v[6:9], v[164:167], v[218:221], v[6:9]
	s_setprio 0
	s_setprio 1
	v_mfma_f32_16x16x32_bf16 v[62:65], v[168:171], v[188:191], 0
	v_mfma_f32_16x16x32_bf16 v[50:53], v[180:183], v[188:191], 0
	v_mfma_f32_16x16x32_bf16 v[46:49], v[168:171], v[196:199], 0
	v_mfma_f32_16x16x32_bf16 v[34:37], v[180:183], v[196:199], 0
	v_mfma_f32_16x16x32_bf16 v[30:33], v[168:171], v[204:207], 0
	v_mfma_f32_16x16x32_bf16 v[18:21], v[180:183], v[204:207], 0
	v_mfma_f32_16x16x32_bf16 v[14:17], v[168:171], v[214:217], 0
	v_mfma_f32_16x16x32_bf16 v[2:5], v[180:183], v[214:217], 0
	v_mfma_f32_16x16x32_bf16 v[62:65], v[172:175], v[192:195], v[62:65]
	v_mfma_f32_16x16x32_bf16 v[50:53], v[184:187], v[192:195], v[50:53]
	v_mfma_f32_16x16x32_bf16 v[46:49], v[172:175], v[200:203], v[46:49]
	v_mfma_f32_16x16x32_bf16 v[34:37], v[184:187], v[200:203], v[34:37]
	v_mfma_f32_16x16x32_bf16 v[30:33], v[172:175], v[210:213], v[30:33]
	v_mfma_f32_16x16x32_bf16 v[18:21], v[184:187], v[210:213], v[18:21]
	v_mfma_f32_16x16x32_bf16 v[14:17], v[172:175], v[218:221], v[14:17]
	v_mfma_f32_16x16x32_bf16 v[2:5], v[184:187], v[218:221], v[2:5]
	s_setprio 0
	s_barrier
	s_add_i32 s56, 0, 0x18000
	s_add_i32 s57, 0, 0x1c000
	v_add_u32_e32 v164, s56, v151
	v_add_u32_e32 v179, s57, v151
	ds_read_b128 v[146:149], v164
	ds_read_b128 v[156:159], v164 offset:1024
	ds_read_b128 v[160:163], v164 offset:2048
	ds_read_b128 v[164:167], v164 offset:3072
	ds_read_b128 v[168:171], v179
	ds_read_b128 v[172:175], v179 offset:1024
	ds_read_b128 v[180:183], v179 offset:2048
	ds_read_b128 v[184:187], v179 offset:3072
	s_add_u32 s28, s28, 0x40000
	s_addc_u32 s29, s29, 0
	s_mov_b32 m0, s39
	v_lshl_add_u64 v[226:227], s[28:29], 0, v[136:137]
	ds_read_b128 v[188:191], v155 offset:32768
	ds_read_b128 v[192:195], v155 offset:33792
	ds_read_b128 v[196:199], v155 offset:34816
	ds_read_b128 v[200:203], v155 offset:35840
	ds_read_b128 v[204:207], v155 offset:36864
	ds_read_b128 v[210:213], v155 offset:37888
	ds_read_b128 v[214:217], v155 offset:38912
	ds_read_b128 v[218:221], v155 offset:39936
	global_load_lds_dwordx4 v[226:227], off
	v_lshl_add_u64 v[226:227], s[28:29], 0, v[132:133]
	s_mov_b32 m0, s40
	s_nop 0
	global_load_lds_dwordx4 v[226:227], off
	s_waitcnt vmcnt(8)
	s_waitcnt lgkmcnt(0)
	s_barrier
	s_setprio 1
	s_waitcnt lgkmcnt(0)
	v_mfma_f32_16x16x32_bf16 v[122:125], v[146:149], v[188:191], v[122:125]
	v_mfma_f32_16x16x32_bf16 v[114:117], v[160:163], v[188:191], v[114:117]
	v_mfma_f32_16x16x32_bf16 v[106:109], v[146:149], v[196:199], v[106:109]
	v_mfma_f32_16x16x32_bf16 v[98:101], v[160:163], v[196:199], v[98:101]
	v_mfma_f32_16x16x32_bf16 v[90:93], v[146:149], v[204:207], v[90:93]
	v_mfma_f32_16x16x32_bf16 v[82:85], v[160:163], v[204:207], v[82:85]
	v_mfma_f32_16x16x32_bf16 v[74:77], v[146:149], v[214:217], v[74:77]
	v_mfma_f32_16x16x32_bf16 v[70:73], v[160:163], v[214:217], v[70:73]
	v_mfma_f32_16x16x32_bf16 v[122:125], v[156:159], v[192:195], v[122:125]
	v_mfma_f32_16x16x32_bf16 v[114:117], v[164:167], v[192:195], v[114:117]
	v_mfma_f32_16x16x32_bf16 v[106:109], v[156:159], v[200:203], v[106:109]
	v_mfma_f32_16x16x32_bf16 v[98:101], v[164:167], v[200:203], v[98:101]
	v_mfma_f32_16x16x32_bf16 v[90:93], v[156:159], v[210:213], v[90:93]
	v_mfma_f32_16x16x32_bf16 v[82:85], v[164:167], v[210:213], v[82:85]
	v_mfma_f32_16x16x32_bf16 v[74:77], v[156:159], v[218:221], v[74:77]
	v_mfma_f32_16x16x32_bf16 v[70:73], v[164:167], v[218:221], v[70:73]
	s_setprio 0
	s_setprio 1
	v_mfma_f32_16x16x32_bf16 v[126:129], v[168:171], v[188:191], v[126:129]
	v_mfma_f32_16x16x32_bf16 v[118:121], v[180:183], v[188:191], v[118:121]
	v_mfma_f32_16x16x32_bf16 v[110:113], v[168:171], v[196:199], v[110:113]
	v_mfma_f32_16x16x32_bf16 v[102:105], v[180:183], v[196:199], v[102:105]
	v_mfma_f32_16x16x32_bf16 v[94:97], v[168:171], v[204:207], v[94:97]
	v_mfma_f32_16x16x32_bf16 v[86:89], v[180:183], v[204:207], v[86:89]
	v_mfma_f32_16x16x32_bf16 v[78:81], v[168:171], v[214:217], v[78:81]
	v_mfma_f32_16x16x32_bf16 v[66:69], v[180:183], v[214:217], v[66:69]
	v_mfma_f32_16x16x32_bf16 v[126:129], v[172:175], v[192:195], v[126:129]
	v_mfma_f32_16x16x32_bf16 v[118:121], v[184:187], v[192:195], v[118:121]
	v_mfma_f32_16x16x32_bf16 v[110:113], v[172:175], v[200:203], v[110:113]
	v_mfma_f32_16x16x32_bf16 v[102:105], v[184:187], v[200:203], v[102:105]
	v_mfma_f32_16x16x32_bf16 v[94:97], v[172:175], v[210:213], v[94:97]
	v_mfma_f32_16x16x32_bf16 v[86:89], v[184:187], v[210:213], v[86:89]
	v_mfma_f32_16x16x32_bf16 v[78:81], v[172:175], v[218:221], v[78:81]
	v_mfma_f32_16x16x32_bf16 v[66:69], v[184:187], v[218:221], v[66:69]
	s_setprio 0
	s_barrier
	s_add_i32 s28, s56, s35
	v_lshl_add_u64 v[176:177], v[176:177], 0, s[10:11]
	s_mov_b32 m0, s28
	ds_read_b128 v[188:191], v155 offset:49152
	ds_read_b128 v[192:195], v155 offset:50176
	ds_read_b128 v[196:199], v155 offset:51200
	ds_read_b128 v[200:203], v155 offset:52224
	ds_read_b128 v[204:207], v155 offset:53248
	ds_read_b128 v[210:213], v155 offset:54272
	ds_read_b128 v[214:217], v155 offset:55296
	ds_read_b128 v[218:221], v155 offset:56320
	global_load_lds_dwordx4 v[176:177], off
	s_add_i32 m0, s28, 0x2000
	s_add_u32 s26, s26, 0x40080
	v_lshl_add_u64 v[176:177], v[208:209], 0, s[10:11]
	s_addc_u32 s27, s27, 0
	s_add_i32 s28, s57, s35
	global_load_lds_dwordx4 v[176:177], off
	v_lshl_add_u64 v[176:177], s[26:27], 0, v[134:135]
	s_mov_b32 m0, s28
	s_nop 0
	global_load_lds_dwordx4 v[176:177], off
	v_lshl_add_u64 v[176:177], s[26:27], 0, v[130:131]
	s_add_i32 m0, s28, 0x2000
	s_nop 0
	global_load_lds_dwordx4 v[176:177], off
	v_lshl_add_u64 v[176:177], v[222:223], 0, s[10:11]
	s_mov_b32 m0, s42
	s_nop 0
	global_load_lds_dwordx4 v[176:177], off
	v_lshl_add_u64 v[176:177], v[224:225], 0, s[10:11]
	s_mov_b32 m0, s43
	s_nop 0
	global_load_lds_dwordx4 v[176:177], off
	s_waitcnt vmcnt(8)
	s_waitcnt lgkmcnt(0)
	s_barrier
	s_setprio 1
	s_waitcnt lgkmcnt(0)
	v_mfma_f32_16x16x32_bf16 v[58:61], v[146:149], v[188:191], v[58:61]
	v_mfma_f32_16x16x32_bf16 v[54:57], v[160:163], v[188:191], v[54:57]
	v_mfma_f32_16x16x32_bf16 v[42:45], v[146:149], v[196:199], v[42:45]
	v_mfma_f32_16x16x32_bf16 v[38:41], v[160:163], v[196:199], v[38:41]
	v_mfma_f32_16x16x32_bf16 v[26:29], v[146:149], v[204:207], v[26:29]
	v_mfma_f32_16x16x32_bf16 v[22:25], v[160:163], v[204:207], v[22:25]
	v_mfma_f32_16x16x32_bf16 v[10:13], v[146:149], v[214:217], v[10:13]
	v_mfma_f32_16x16x32_bf16 v[6:9], v[160:163], v[214:217], v[6:9]
	v_mfma_f32_16x16x32_bf16 v[58:61], v[156:159], v[192:195], v[58:61]
	v_mfma_f32_16x16x32_bf16 v[54:57], v[164:167], v[192:195], v[54:57]
	v_mfma_f32_16x16x32_bf16 v[42:45], v[156:159], v[200:203], v[42:45]
	v_mfma_f32_16x16x32_bf16 v[38:41], v[164:167], v[200:203], v[38:41]
	v_mfma_f32_16x16x32_bf16 v[26:29], v[156:159], v[210:213], v[26:29]
	v_mfma_f32_16x16x32_bf16 v[22:25], v[164:167], v[210:213], v[22:25]
	v_mfma_f32_16x16x32_bf16 v[10:13], v[156:159], v[218:221], v[10:13]
	v_mfma_f32_16x16x32_bf16 v[6:9], v[164:167], v[218:221], v[6:9]
	s_setprio 0
	s_setprio 1
	v_mfma_f32_16x16x32_bf16 v[62:65], v[168:171], v[188:191], v[62:65]
	v_mfma_f32_16x16x32_bf16 v[50:53], v[180:183], v[188:191], v[50:53]
	v_mfma_f32_16x16x32_bf16 v[46:49], v[168:171], v[196:199], v[46:49]
	v_mfma_f32_16x16x32_bf16 v[34:37], v[180:183], v[196:199], v[34:37]
	v_mfma_f32_16x16x32_bf16 v[30:33], v[168:171], v[204:207], v[30:33]
	v_mfma_f32_16x16x32_bf16 v[18:21], v[180:183], v[204:207], v[18:21]
	v_mfma_f32_16x16x32_bf16 v[14:17], v[168:171], v[214:217], v[14:17]
	v_mfma_f32_16x16x32_bf16 v[2:5], v[180:183], v[214:217], v[2:5]
	v_mfma_f32_16x16x32_bf16 v[62:65], v[172:175], v[192:195], v[62:65]
	v_mfma_f32_16x16x32_bf16 v[50:53], v[184:187], v[192:195], v[50:53]
	v_mfma_f32_16x16x32_bf16 v[46:49], v[172:175], v[200:203], v[46:49]
	v_mfma_f32_16x16x32_bf16 v[34:37], v[184:187], v[200:203], v[34:37]
	v_mfma_f32_16x16x32_bf16 v[30:33], v[172:175], v[210:213], v[30:33]
	v_mfma_f32_16x16x32_bf16 v[18:21], v[184:187], v[210:213], v[18:21]
	v_mfma_f32_16x16x32_bf16 v[14:17], v[172:175], v[218:221], v[14:17]
	v_mfma_f32_16x16x32_bf16 v[2:5], v[184:187], v[218:221], v[2:5]
	s_setprio 0
	s_barrier
	s_add_i32 s55, s55, 2
	s_add_u32 s24, s24, 0x100
	s_addc_u32 s25, s25, 0
	s_add_u32 s53, s53, 0x100
	s_addc_u32 s54, s54, 0
	s_cmp_gt_u32 s55, 13
